# attention: second units taken from a per-layer queue in largest-first order (atomic ticket when a unit's last tile is done) instead of the static pairing; evens out workgroups running at different spe
# speedup vs baseline: 1.0151x; 1.0151x over previous
;   __device__ __forceinline__ bool next(int i,AttnUnit&u)const{ if(i>=2)return false; const int s=vcu&15; u.bh=vcu>>4; u.qb=(i==0)?31-s:s; return true; }
;   AttnUnit u;
;   for(int i=0;S.next(i,u);++i){ S.a_ready(u); attn_unit<THRL>(u.bh>>3,u.bh&7,u.qb,T.Q,T.K,T.V,T.O,lds); S.done(u); }
.LBB0_574:
	v_mov_b32_e32 v241, 0xe0000
	s_and_b64 vcc, exec, s[74:75]
	v_readlane_b32 s30, v252, 0
	s_and_b32 s99, s30, 15
	s_xor_b32 s99, s99, 31
	s_waitcnt vmcnt(63) expcnt(7) lgkmcnt(15)
	s_barrier
	s_cbranch_vccz .LBB0_581

; __device__ __forceinline__ int crow(int r,int hi){return (r&3)+8*(r>>2)+4*hi;}
; template<int THRL> __device__ __forceinline__ void attn_unit(int b,int h,int qb,const bf16*Q,const bf16*__restrict__ K,const bf16*__restrict__ V,bf16*O,char*shm){
;   int tid_l=threadIdx.x; asm volatile("":"+v"(tid_l)); const int tid=tid_l,lane=tid&63,r32=lane&31,hi=lane>>5; const int wid=__builtin_amdgcn_readfirstlane(tid>>6);
;   const long rowbase=(long)b*SEQ; const int q0=qb*QB;
;   const int hh_=h>>1,mm_=h&1; const bf16*Qw=Q+(rowbase+q0+wid*QBLK)*PQ+QCOL+hh_*128+mm_*64;
;   const bf16*Kh=K+rowbase*PQ+KCOL+hh_*128+mm_*64,*Vh=V+rowbase*PQ+VCOL+hh_*128;
;     ...
;   {auto rr=__builtin_amdgcn_permlane32_swap(__float_as_uint(l_reg),__float_as_uint(l_reg),false,false);l_reg=__uint_as_float(rr[0])+__uint_as_float(rr[1]);}
;   if(hi==0)wsf[32+r32]=l_reg;asm volatile("s_waitcnt lgkmcnt(0)":::"memory");
;   float rli[16];
;   #pragma unroll
;   for(int r=0;r<16;++r)rli[r]=__builtin_amdgcn_rcpf(wsf[32+crow(r,hi)]);
;   bf16*Ow=O+(rowbase+q0+wid*QBLK)*DM+hh_*256+mm_*128;
;   #pragma unroll
;   for(int half=0;half<2;++half)
;   { bf16*stg=(bf16*)(shm+LDS_OST)+wid*2048;
;     #pragma unroll
;     for(int r=0;r<16;++r){const int orow=crow(r,hi);
;       #pragma unroll
;       for(int d0=0;d0<2;++d0)stg[orow*64+d0*32+r32]=__float2bfloat16(o[2*half+d0][r]*rli[r]);}
;     asm volatile("s_waitcnt lgkmcnt(0)":::"memory");
;     #pragma unroll
;     for(int i=0;i<4;++i){const int row=i*8+(lane>>3),ch=lane&7; const u32x4 v=*(const u32x4*)(stg+row*64+ch*8); ATTN_STORE16(Ow+(long)row*DM+half*64+ch*8,v);}
.LBB0_581:
	s_ashr_i32 s0, s30, 7
	s_ashr_i32 s2, s30, 4
	s_ashr_i32 s1, s0, 31
	s_and_b32 s31, s30, 15
	s_lshl_b64 s[10:11], s[0:1], 13
	s_bfe_u32 s1, s2, 0x20001
	s_and_b32 s2, s2, 1
	s_mov_b32 s14, s99
	s_lshl_b32 s3, s1, 8
	s_lshl_b32 s8, s2, 7
	s_lshl_b32 s1, s1, 9
	v_readlane_b32 s9, v253, 19
	s_add_u32 s1, s9, s1
	v_readlane_b32 s9, v253, 20
	s_addc_u32 s9, s9, 0
	s_lshl_b32 s2, s2, 8
	s_add_u32 s36, s1, s2
	s_addc_u32 s37, s9, 0
	s_mul_hi_i32 s1, s0, 0x3800000
	s_mul_i32 s0, s0, 0x3800000
	s_add_u32 s2, s60, s0
	s_addc_u32 s9, s61, s1
	s_add_u32 s2, s2, s3
	s_addc_u32 s9, s9, 0
	s_add_u32 s12, s2, s8
	s_addc_u32 s13, s9, 0
	s_add_u32 s12, s12, 0x1000
	s_addc_u32 s13, s13, 0
	s_add_u32 s20, s2, 0x1400
	s_addc_u32 s21, s9, 0
	s_add_u32 s2, s60, s3
	s_addc_u32 s9, s61, 0
	s_add_u32 s48, s2, s8
	s_addc_u32 s49, s9, 0
	s_or_b32 s0, s0, s3
	s_add_u32 s24, s68, s0
	s_addc_u32 s25, s69, s1
	s_mov_b64 s[38:39], -1
	s_branch .LBB0_583
.LBB0_582:
	s_or_b64 exec, exec, s[0:1]
	s_cmp_lg_u32 s52, 0
	s_cbranch_scc1 .Lmy_at_noq
	v_readlane_b32 s0, v254, 44
	s_lshl_b32 s0, s0, 8
	s_addk_i32 s0, 0x3b00
	s_add_u32 s0, s68, s0
	s_addc_u32 s1, s69, 0
	v_mov_b32_e32 v150, 1
	s_mov_b64 s[98:99], exec
	s_mov_b64 exec, 1
	global_atomic_add v150, v221, v150, s[0:1] sc0
	s_mov_b64 exec, s[98:99]
.Lmy_at_noq:
	s_waitcnt lgkmcnt(0)
	ds_read_b128 v[64:67], v96 offset:128
	ds_read_b128 v[68:71], v96 offset:160
	s_lshl_b64 s[0:1], s[40:41], 11
	s_add_u32 s0, s36, s0
	s_addc_u32 s1, s37, s1
	s_waitcnt lgkmcnt(1)
	v_rcp_f32_e32 v72, v64
	s_lshl_b32 s2, s52, 12
	s_add_i32 s2, s2, 0
	s_add_i32 s2, s2, 0x12800
	v_rcp_f32_e32 v73, v65
	v_lshl_add_u32 v82, v243, 1, s2
	v_lshlrev_b32_e32 v86, 7, v245
	v_mul_f32_e32 v32, v32, v72
	v_add_u32_e32 v87, v82, v86
	v_cvt_pk_bf16_f32 v32, v32, s0
	v_rcp_f32_e32 v74, v66
	v_rcp_f32_e32 v75, v67
	s_waitcnt lgkmcnt(0)
	v_rcp_f32_e32 v76, v68
	ds_read_b128 v[64:67], v96 offset:192
	v_rcp_f32_e32 v77, v69
	v_rcp_f32_e32 v78, v70
	v_rcp_f32_e32 v79, v71
	ds_read_b128 v[68:71], v96 offset:224
	ds_write_b16 v87, v32
	v_mul_f32_e32 v32, v48, v72
	v_cvt_pk_bf16_f32 v32, v32, s0
	ds_write_b16 v87, v32 offset:64
	v_mul_f32_e32 v32, v33, v73
	v_cvt_pk_bf16_f32 v32, v32, s0
	ds_write_b16 v87, v32 offset:128
	v_mul_f32_e32 v32, v49, v73
	v_cvt_pk_bf16_f32 v32, v32, s0
	ds_write_b16 v87, v32 offset:192
	v_mul_f32_e32 v32, v34, v74
	v_cvt_pk_bf16_f32 v32, v32, s0
	ds_write_b16 v87, v32 offset:256
	v_mul_f32_e32 v32, v50, v74
	v_cvt_pk_bf16_f32 v32, v32, s0
	ds_write_b16 v87, v32 offset:320
	v_mul_f32_e32 v32, v35, v75
	v_cvt_pk_bf16_f32 v32, v32, s0
	ds_write_b16 v87, v32 offset:384
	v_mul_f32_e32 v32, v51, v75
	v_cvt_pk_bf16_f32 v32, v32, s0
	ds_write_b16 v87, v32 offset:448
	v_or_b32_e32 v32, 0x400, v86
	v_add_u32_e32 v48, v82, v32
	v_mul_f32_e32 v32, v36, v76
	v_cvt_pk_bf16_f32 v32, v32, s0
	ds_write_b16 v48, v32
	v_mul_f32_e32 v32, v52, v76
	v_cvt_pk_bf16_f32 v32, v32, s0
	ds_write_b16 v48, v32 offset:64
	v_or_b32_e32 v32, 0x480, v86
	v_add_u32_e32 v49, v82, v32
	v_mul_f32_e32 v32, v37, v77
	v_cvt_pk_bf16_f32 v32, v32, s0
	ds_write_b16 v49, v32
	v_mul_f32_e32 v32, v53, v77
	v_cvt_pk_bf16_f32 v32, v32, s0
	ds_write_b16 v49, v32 offset:64
	v_or_b32_e32 v32, 0x500, v86
	v_add_u32_e32 v50, v82, v32
	v_mul_f32_e32 v32, v38, v78
	v_cvt_pk_bf16_f32 v32, v32, s0
	ds_write_b16 v50, v32
	v_mul_f32_e32 v32, v54, v78
	v_cvt_pk_bf16_f32 v32, v32, s0
	ds_write_b16 v50, v32 offset:64
	v_or_b32_e32 v32, 0x580, v86
	v_add_u32_e32 v51, v82, v32
	v_mul_f32_e32 v32, v39, v79
	s_waitcnt lgkmcnt(14)
	v_rcp_f32_e32 v80, v64
	v_cvt_pk_bf16_f32 v32, v32, s0
	ds_write_b16 v51, v32
	v_mul_f32_e32 v32, v55, v79
	v_cvt_pk_bf16_f32 v32, v32, s0
	ds_write_b16 v51, v32 offset:64
	v_or_b32_e32 v32, 0x800, v86
	v_add_u32_e32 v52, v82, v32
	v_mul_f32_e32 v32, v40, v80
	v_rcp_f32_e32 v81, v65
	v_cvt_pk_bf16_f32 v32, v32, s0
	ds_write_b16 v52, v32
	v_mul_f32_e32 v32, v56, v80
	v_cvt_pk_bf16_f32 v32, v32, s0
	ds_write_b16 v52, v32 offset:64
	v_or_b32_e32 v32, 0x880, v86
	v_add_u32_e32 v53, v82, v32
	v_mul_f32_e32 v32, v41, v81
	v_rcp_f32_e32 v66, v66
	v_cvt_pk_bf16_f32 v32, v32, s0
	ds_write_b16 v53, v32
	v_mul_f32_e32 v32, v57, v81
	v_cvt_pk_bf16_f32 v32, v32, s0
	ds_write_b16 v53, v32 offset:64
	v_or_b32_e32 v32, 0x900, v86
	v_add_u32_e32 v54, v82, v32
	v_mul_f32_e32 v32, v42, v66
	v_rcp_f32_e32 v67, v67
	v_cvt_pk_bf16_f32 v32, v32, s0
	ds_write_b16 v54, v32
	v_mul_f32_e32 v32, v58, v66
	v_cvt_pk_bf16_f32 v32, v32, s0
	ds_write_b16 v54, v32 offset:64
	v_or_b32_e32 v32, 0x980, v86
	v_add_u32_e32 v55, v82, v32
	v_mul_f32_e32 v32, v43, v67
	v_rcp_f32_e32 v68, v68
	v_cvt_pk_bf16_f32 v32, v32, s0
	ds_write_b16 v55, v32
	v_mul_f32_e32 v32, v59, v67
	v_cvt_pk_bf16_f32 v32, v32, s0
	ds_write_b16 v55, v32 offset:64
	v_or_b32_e32 v32, 0xc00, v86
	v_add_u32_e32 v56, v82, v32
	v_mul_f32_e32 v32, v44, v68
	v_rcp_f32_e32 v69, v69
	v_cvt_pk_bf16_f32 v32, v32, s0
	ds_write_b16 v56, v32
	v_mul_f32_e32 v32, v60, v68
	v_cvt_pk_bf16_f32 v32, v32, s0
	ds_write_b16 v56, v32 offset:64
	v_or_b32_e32 v32, 0xc80, v86
	v_add_u32_e32 v57, v82, v32
	v_mul_f32_e32 v32, v45, v69
	v_rcp_f32_e32 v70, v70
	v_cvt_pk_bf16_f32 v32, v32, s0
	ds_write_b16 v57, v32
	v_mul_f32_e32 v32, v61, v69
	v_cvt_pk_bf16_f32 v32, v32, s0
	ds_write_b16 v57, v32 offset:64
	v_or_b32_e32 v32, 0xd00, v86
	v_add_u32_e32 v58, v82, v32
	v_mul_f32_e32 v32, v46, v70
	v_rcp_f32_e32 v71, v71
	v_cvt_pk_bf16_f32 v32, v32, s0
	ds_write_b16 v58, v32
	v_mul_f32_e32 v32, v62, v70
	v_cvt_pk_bf16_f32 v32, v32, s0
	ds_write_b16 v58, v32 offset:64
	v_or_b32_e32 v32, 0xd80, v86
	v_add_u32_e32 v46, v82, v32
	v_mul_f32_e32 v32, v47, v71
	v_cvt_pk_bf16_f32 v32, v32, s0
	v_lshlrev_b32_e32 v64, 1, v244
	ds_write_b16 v46, v32
	v_mul_f32_e32 v32, v63, v71
	v_lshrrev_b32_e32 v83, 3, v242
	v_and_b32_e32 v220, 0x70, v64
	v_cvt_pk_bf16_f32 v32, v32, s0
	v_add_u32_e32 v84, s2, v220
	ds_write_b16 v46, v32 offset:64
	v_or_b32_e32 v42, 8, v83
	v_lshl_add_u32 v85, v83, 7, v84
	s_waitcnt lgkmcnt(0)
; __device__ __forceinline__ int crow(int r,int hi){return (r&3)+8*(r>>2)+4*hi;}
;   __device__ __forceinline__ bool next(int i,AttnUnit&u)const{ if(i>=2)return false; const int s=vcu&15; u.bh=vcu>>4; u.qb=(i==0)?31-s:s; return true; }
; template<int THRL> __device__ __forceinline__ void attn_unit(int b,int h,int qb,const bf16*Q,const bf16*__restrict__ K,const bf16*__restrict__ V,bf16*O,char*shm){
;     ...
;   { bf16*stg=(bf16*)(shm+LDS_OST)+wid*2048;
;     #pragma unroll
;     for(int r=0;r<16;++r){const int orow=crow(r,hi);
;       #pragma unroll
;       for(int d0=0;d0<2;++d0)stg[orow*64+d0*32+r32]=__float2bfloat16(o[2*half+d0][r]*rli[r]);}
;     asm volatile("s_waitcnt lgkmcnt(0)":::"memory");
;     #pragma unroll
;     for(int i=0;i<4;++i){const int row=i*8+(lane>>3),ch=lane&7; const u32x4 v=*(const u32x4*)(stg+row*64+ch*8); ATTN_STORE16(Ow+(long)row*DM+half*64+ch*8,v);}
;     asm volatile("s_waitcnt lgkmcnt(0)":::"memory"); }
;   asm volatile("s_waitcnt lgkmcnt(0)\n\ts_barrier":::"memory");
;   AttnUnit u;
;   for(int i=0;S.next(i,u);++i){ S.a_ready(u); attn_unit<THRL>(u.bh>>3,u.bh&7,u.qb,T.Q,T.K,T.V,T.O,lds); S.done(u); }
	v_lshl_add_u32 v47, v42, 7, v84
	ds_read_b128 v[32:35], v85
	ds_read_b128 v[36:39], v47
	v_lshl_add_u64 v[64:65], s[0:1], 0, v[220:221]
	v_lshlrev_b32_e32 v220, 11, v83
	v_lshl_add_u64 v[40:41], v[64:65], 0, v[220:221]
	v_lshlrev_b32_e32 v220, 11, v42
	v_lshl_add_u64 v[42:43], v[64:65], 0, v[220:221]
	s_waitcnt lgkmcnt(0)
	global_store_dwordx4 v[42:43], v[36:39], off
	v_or_b32_e32 v60, 24, v83
	global_store_dwordx4 v[40:41], v[32:35], off
	v_or_b32_e32 v36, 16, v83
	v_lshl_add_u32 v59, v36, 7, v84
	ds_read_b128 v[32:35], v59
	v_lshl_add_u32 v61, v60, 7, v84
	v_lshlrev_b32_e32 v220, 11, v36
	ds_read_b128 v[36:39], v61
	v_lshl_add_u64 v[44:45], v[64:65], 0, v[220:221]
	v_lshlrev_b32_e32 v220, 11, v60
	s_waitcnt lgkmcnt(1)
	global_store_dwordx4 v[44:45], v[32:35], off
	v_mul_f32_e32 v0, v0, v72
	v_cvt_pk_bf16_f32 v0, v0, s0
	v_lshl_add_u64 v[32:33], v[64:65], 0, v[220:221]
	s_waitcnt lgkmcnt(0)
	global_store_dwordx4 v[32:33], v[36:39], off
	s_waitcnt lgkmcnt(0)
	ds_write_b16 v87, v0 offset:64
	v_mul_f32_e32 v0, v17, v73
	v_cvt_pk_bf16_f32 v0, v0, s0
	ds_write_b16 v87, v0 offset:128
	v_mul_f32_e32 v0, v1, v73
	v_cvt_pk_bf16_f32 v0, v0, s0
	ds_write_b16 v87, v0 offset:192
	v_mul_f32_e32 v0, v18, v74
	v_cvt_pk_bf16_f32 v0, v0, s0
	ds_write_b16 v87, v0 offset:256
	v_mul_f32_e32 v0, v2, v74
	v_cvt_pk_bf16_f32 v0, v0, s0
	ds_write_b16 v87, v0 offset:320
	v_mul_f32_e32 v0, v19, v75
	v_cvt_pk_bf16_f32 v0, v0, s0
	ds_write_b16 v87, v0 offset:384
	v_mul_f32_e32 v0, v3, v75
	v_cvt_pk_bf16_f32 v0, v0, s0
	v_mul_f32_e32 v16, v16, v72
	ds_write_b16 v87, v0 offset:448
	v_mul_f32_e32 v0, v20, v76
	v_cvt_pk_bf16_f32 v16, v16, s0
	v_cvt_pk_bf16_f32 v0, v0, s0
	ds_write_b16 v87, v16
	ds_write_b16 v48, v0
	v_mul_f32_e32 v0, v4, v76
	v_cvt_pk_bf16_f32 v0, v0, s0
	ds_write_b16 v48, v0 offset:64
	v_mul_f32_e32 v0, v21, v77
	v_cvt_pk_bf16_f32 v0, v0, s0
	ds_write_b16 v49, v0
	v_mul_f32_e32 v0, v5, v77
	v_cvt_pk_bf16_f32 v0, v0, s0
	ds_write_b16 v49, v0 offset:64
	v_mul_f32_e32 v0, v22, v78
	v_cvt_pk_bf16_f32 v0, v0, s0
	ds_write_b16 v50, v0
	v_mul_f32_e32 v0, v6, v78
	v_cvt_pk_bf16_f32 v0, v0, s0
	ds_write_b16 v50, v0 offset:64
	v_mul_f32_e32 v0, v23, v79
	v_cvt_pk_bf16_f32 v0, v0, s0
	ds_write_b16 v51, v0
	v_mul_f32_e32 v0, v7, v79
	v_cvt_pk_bf16_f32 v0, v0, s0
	ds_write_b16 v51, v0 offset:64
	v_mul_f32_e32 v0, v24, v80
	v_cvt_pk_bf16_f32 v0, v0, s0
	ds_write_b16 v52, v0
	v_mul_f32_e32 v0, v8, v80
	v_cvt_pk_bf16_f32 v0, v0, s0
	ds_write_b16 v52, v0 offset:64
	v_mul_f32_e32 v0, v25, v81
	v_cvt_pk_bf16_f32 v0, v0, s0
	ds_write_b16 v53, v0
	v_mul_f32_e32 v0, v9, v81
	v_cvt_pk_bf16_f32 v0, v0, s0
	ds_write_b16 v53, v0 offset:64
	v_mul_f32_e32 v0, v26, v66
	v_cvt_pk_bf16_f32 v0, v0, s0
	ds_write_b16 v54, v0
	v_mul_f32_e32 v0, v10, v66
	v_cvt_pk_bf16_f32 v0, v0, s0
	ds_write_b16 v54, v0 offset:64
	v_mul_f32_e32 v0, v27, v67
	v_cvt_pk_bf16_f32 v0, v0, s0
	ds_write_b16 v55, v0
	v_mul_f32_e32 v0, v11, v67
	v_cvt_pk_bf16_f32 v0, v0, s0
	ds_write_b16 v55, v0 offset:64
	v_mul_f32_e32 v0, v28, v68
	v_cvt_pk_bf16_f32 v0, v0, s0
	ds_write_b16 v56, v0
	v_mul_f32_e32 v0, v12, v68
	v_cvt_pk_bf16_f32 v0, v0, s0
	ds_write_b16 v56, v0 offset:64
	v_mul_f32_e32 v0, v29, v69
	v_cvt_pk_bf16_f32 v0, v0, s0
	ds_write_b16 v57, v0
	v_mul_f32_e32 v0, v13, v69
	v_cvt_pk_bf16_f32 v0, v0, s0
	ds_write_b16 v57, v0 offset:64
	v_mul_f32_e32 v0, v30, v70
	v_cvt_pk_bf16_f32 v0, v0, s0
	ds_write_b16 v58, v0
	v_mul_f32_e32 v0, v14, v70
	v_cvt_pk_bf16_f32 v0, v0, s0
	ds_write_b16 v58, v0 offset:64
	v_mul_f32_e32 v0, v31, v71
	v_cvt_pk_bf16_f32 v0, v0, s0
	ds_write_b16 v46, v0
	v_mul_f32_e32 v0, v15, v71
	v_cvt_pk_bf16_f32 v0, v0, s0
	ds_write_b16 v46, v0 offset:64
	s_waitcnt lgkmcnt(0)
	ds_read_b128 v[0:3], v85
	ds_read_b128 v[4:7], v47
	ds_read_b128 v[8:11], v59
	ds_read_b128 v[12:15], v61
	s_waitcnt lgkmcnt(3)
	global_store_dwordx4 v[40:41], v[0:3], off offset:128
	s_waitcnt lgkmcnt(2)
	global_store_dwordx4 v[42:43], v[4:7], off offset:128
	s_waitcnt lgkmcnt(1)
	global_store_dwordx4 v[44:45], v[8:11], off offset:128
	s_waitcnt lgkmcnt(0)
	global_store_dwordx4 v[32:33], v[12:15], off offset:128
	s_waitcnt lgkmcnt(0)
	s_waitcnt lgkmcnt(0)
	s_barrier
	s_cmp_lg_u32 s52, 0
	s_cbranch_scc1 .Lmy_at_w
	s_waitcnt vmcnt(8)
	v_readfirstlane_b32 s98, v150
	v_mov_b32_e32 v1, 0x23f40
	s_nop 0
	v_mov_b32_e32 v0, s98
	ds_write_b32 v1, v0
	s_waitcnt lgkmcnt(0)
.Lmy_at_w:
	s_barrier
	v_mov_b32_e32 v1, 0x23f40
	ds_read_b32 v0, v1
	s_waitcnt lgkmcnt(0)
	v_readfirstlane_b32 s98, v0
	s_cmpk_gt_u32 s98, 0xff
	s_cbranch_scc1 .LBB0_575
	s_lshr_b32 s99, s98, 4
	s_sub_i32 s99, 15, s99
	s_and_b32 s30, s98, 15
	s_lshl_b32 s30, s30, 4
	s_branch .LBB0_581
